# P1 epilogues (plain and scaled): LDS transpose read-back into fresh regs, stores deferred one piece
# baseline (speedup 1.0000x reference)
; __device__ __forceinline__ size_t tm_block(int pm, int ct, int nct) { return ((size_t)pm * nct + ct) * 32768; }
; __device__ __forceinline__ u32x4 pack8(const f32x4& v0, const f32x4& v1) { u32x4 w; w.x = cvt_pk_bf16(v0[0], v0[1]); w.y = cvt_pk_bf16(v0[2], v0[3]); w.z = cvt_pk_bf16(v1[0], v1[1]); w.w = cvt_pk_bf16(v1[2], v1[3]); return w; }
;     __device__ __forceinline__ void operator()(const f32x4 (&acc)[2][2][4][2], const Unit& u, int wr, int wc, int fr, int fq) const {
;         const PieceOut po(scr, O, tm_block(u.pm, u.pn * 4 + wc, nct), wr, wc, fr, fq);
;         const float qs = (u.pn < 2 || u.pn == 3 || u.pn == 4) ? 0.125f * 1.4426950408889634f : 1.0f;
; #pragma unroll
;         for (int ai = 0; ai < 2; ++ai)
; #pragma unroll
;             for (int m = 0; m < 4; ++m) { po.put(0, pack8(acc[ai][0][m][0] * qs, acc[ai][0][m][1] * qs)); po.put(1, pack8(acc[ai][1][m][0] * qs, acc[ai][1][m][1] * qs)); po.flush<true>(ai, m); }
;     }
.LBB0_153:
	s_lshl_b32 s15, s70, 2
	s_or_b32 s15, s15, s53
	s_mul_hi_i32 s17, s22, 0x44
	s_mulk_i32 s22, 0x44
	s_ashr_i32 s25, s15, 31
	s_add_u32 s24, s22, s15
	s_addc_u32 s25, s17, s25
	s_lshl_b64 s[24:25], s[24:25], 15
	s_cmp_lt_i32 s70, 2
	s_cselect_b64 s[26:27], -1, 0
	s_add_i32 s15, s70, -3
	s_cmp_lt_u32 s15, 2
	s_cselect_b64 s[28:29], -1, 0
	s_or_b64 vcc, s[26:27], s[28:29]
	s_cbranch_vccz .Lp1_epi_plain
	v_cndmask_b32_e32 v148, 1.0, v155, vcc
	v_pk_mul_f32 v[128:129], v[148:149], v[128:129] op_sel_hi:[0,1]
	v_pk_mul_f32 v[126:127], v[148:149], v[126:127] op_sel_hi:[0,1]
	v_pk_mul_f32 v[156:157], v[148:149], v[124:125] op_sel_hi:[0,1]
	v_pk_mul_f32 v[124:125], v[148:149], v[122:123] op_sel_hi:[0,1]
	v_cvt_pk_bf16_f32 v122, v126, v127
	v_cvt_pk_bf16_f32 v123, v128, v129
	v_cvt_pk_bf16_f32 v124, v124, v125
	v_cvt_pk_bf16_f32 v125, v156, v157
	ds_write_b128 v153, v[122:125]
	v_pk_mul_f32 v[122:123], v[148:149], v[112:113] op_sel_hi:[0,1]
	v_pk_mul_f32 v[112:113], v[148:149], v[110:111] op_sel_hi:[0,1]
	v_pk_mul_f32 v[120:121], v[148:149], v[120:121] op_sel_hi:[0,1]
	v_pk_mul_f32 v[118:119], v[148:149], v[118:119] op_sel_hi:[0,1]
	v_cvt_pk_bf16_f32 v110, v118, v119
	v_cvt_pk_bf16_f32 v111, v120, v121
	v_cvt_pk_bf16_f32 v112, v112, v113
	v_cvt_pk_bf16_f32 v113, v122, v123
	ds_write_b128 v153, v[110:113] offset:64
	ds_read_b128 v[160:163], v154
	ds_read_b128 v[164:167], v154 offset:1152
	v_lshl_add_u64 v[122:123], v[138:139], 0, s[24:25]
	v_pk_mul_f32 v[110:111], v[148:149], v[116:117] op_sel_hi:[0,1]
	v_pk_mul_f32 v[112:113], v[148:149], v[114:115] op_sel_hi:[0,1]
	v_pk_mul_f32 v[114:115], v[148:149], v[108:109] op_sel_hi:[0,1]
	v_pk_mul_f32 v[108:109], v[148:149], v[106:107] op_sel_hi:[0,1]
	v_cvt_pk_bf16_f32 v106, v112, v113
	v_cvt_pk_bf16_f32 v107, v110, v111
	v_cvt_pk_bf16_f32 v108, v108, v109
	v_cvt_pk_bf16_f32 v109, v114, v115
	ds_write_b128 v153, v[106:109]
	v_pk_mul_f32 v[106:107], v[148:149], v[96:97] op_sel_hi:[0,1]
	v_pk_mul_f32 v[96:97], v[148:149], v[94:95] op_sel_hi:[0,1]
	v_pk_mul_f32 v[104:105], v[148:149], v[104:105] op_sel_hi:[0,1]
	v_pk_mul_f32 v[102:103], v[148:149], v[102:103] op_sel_hi:[0,1]
	v_cvt_pk_bf16_f32 v94, v102, v103
	v_cvt_pk_bf16_f32 v95, v104, v105
	v_cvt_pk_bf16_f32 v96, v96, v97
	v_cvt_pk_bf16_f32 v97, v106, v107
	ds_write_b128 v153, v[94:97] offset:64
	s_waitcnt lgkmcnt(2)
	global_store_dwordx4 v[122:123], v[160:163], off nt
	global_store_dwordx4 v[122:123], v[164:167], off offset:1024 nt
	ds_read_b128 v[168:171], v154
	ds_read_b128 v[172:175], v154 offset:1152
	v_pk_mul_f32 v[94:95], v[148:149], v[100:101] op_sel_hi:[0,1]
	v_pk_mul_f32 v[96:97], v[148:149], v[98:99] op_sel_hi:[0,1]
	v_pk_mul_f32 v[98:99], v[148:149], v[92:93] op_sel_hi:[0,1]
	v_pk_mul_f32 v[92:93], v[148:149], v[90:91] op_sel_hi:[0,1]
	v_cvt_pk_bf16_f32 v90, v96, v97
	v_cvt_pk_bf16_f32 v91, v94, v95
	v_cvt_pk_bf16_f32 v92, v92, v93
	v_cvt_pk_bf16_f32 v93, v98, v99
	ds_write_b128 v153, v[90:93]
	v_pk_mul_f32 v[90:91], v[148:149], v[84:85] op_sel_hi:[0,1]
	v_pk_mul_f32 v[84:85], v[148:149], v[82:83] op_sel_hi:[0,1]
	v_pk_mul_f32 v[88:89], v[148:149], v[88:89] op_sel_hi:[0,1]
	v_pk_mul_f32 v[86:87], v[148:149], v[86:87] op_sel_hi:[0,1]
	v_cvt_pk_bf16_f32 v82, v86, v87
	v_cvt_pk_bf16_f32 v83, v88, v89
	v_cvt_pk_bf16_f32 v84, v84, v85
	v_cvt_pk_bf16_f32 v85, v90, v91
	ds_write_b128 v153, v[82:85] offset:64
	s_waitcnt lgkmcnt(2)
	global_store_dwordx4 v[122:123], v[168:171], off offset:2048 nt
	global_store_dwordx4 v[122:123], v[172:175], off offset:3072 nt
	ds_read_b128 v[160:163], v154
	ds_read_b128 v[164:167], v154 offset:1152
	v_add_co_u32_e32 v90, vcc, s58, v122
	v_pk_mul_f32 v[80:81], v[148:149], v[80:81] op_sel_hi:[0,1]
	s_nop 0
	v_addc_co_u32_e32 v91, vcc, 0, v123, vcc
	v_pk_mul_f32 v[78:79], v[148:149], v[78:79] op_sel_hi:[0,1]
	v_pk_mul_f32 v[82:83], v[148:149], v[76:77] op_sel_hi:[0,1]
	v_pk_mul_f32 v[76:77], v[148:149], v[74:75] op_sel_hi:[0,1]
	v_cvt_pk_bf16_f32 v74, v78, v79
	v_cvt_pk_bf16_f32 v75, v80, v81
	v_cvt_pk_bf16_f32 v76, v76, v77
	v_cvt_pk_bf16_f32 v77, v82, v83
	ds_write_b128 v153, v[74:77]
	v_pk_mul_f32 v[74:75], v[148:149], v[68:69] op_sel_hi:[0,1]
	v_pk_mul_f32 v[68:69], v[148:149], v[66:67] op_sel_hi:[0,1]
	v_pk_mul_f32 v[72:73], v[148:149], v[72:73] op_sel_hi:[0,1]
	v_pk_mul_f32 v[70:71], v[148:149], v[70:71] op_sel_hi:[0,1]
	v_cvt_pk_bf16_f32 v66, v70, v71
	v_cvt_pk_bf16_f32 v67, v72, v73
	v_cvt_pk_bf16_f32 v68, v68, v69
	v_cvt_pk_bf16_f32 v69, v74, v75
	ds_write_b128 v153, v[66:69] offset:64
	s_waitcnt lgkmcnt(2)
; __device__ __forceinline__ size_t tm_block(int pm, int ct, int nct) { return ((size_t)pm * nct + ct) * 32768; }
; __device__ __forceinline__ u32x4 pack8(const f32x4& v0, const f32x4& v1) { u32x4 w; w.x = cvt_pk_bf16(v0[0], v0[1]); w.y = cvt_pk_bf16(v0[2], v0[3]); w.z = cvt_pk_bf16(v1[0], v1[1]); w.w = cvt_pk_bf16(v1[2], v1[3]); return w; }
;     __device__ __forceinline__ void operator()(const f32x4 (&acc)[2][2][4][2], const Unit& u, int wr, int wc, int fr, int fq) const {
;         const PieceOut po(scr, O, tm_block(u.pm, u.pn * 4 + wc, nct), wr, wc, fr, fq);
;         const float qs = (u.pn < 2 || u.pn == 3 || u.pn == 4) ? 0.125f * 1.4426950408889634f : 1.0f;
; #pragma unroll
;         for (int ai = 0; ai < 2; ++ai)
; #pragma unroll
;             for (int m = 0; m < 4; ++m) { po.put(0, pack8(acc[ai][0][m][0] * qs, acc[ai][0][m][1] * qs)); po.put(1, pack8(acc[ai][1][m][0] * qs, acc[ai][1][m][1] * qs)); po.flush<true>(ai, m); }
;     }
	global_store_dwordx4 v[90:91], v[160:163], off nt
	global_store_dwordx4 v[90:91], v[164:167], off offset:1024 nt
	ds_read_b128 v[168:171], v154
	ds_read_b128 v[172:175], v154 offset:1152
	v_pk_mul_f32 v[64:65], v[148:149], v[64:65] op_sel_hi:[0,1]
	v_pk_mul_f32 v[62:63], v[148:149], v[62:63] op_sel_hi:[0,1]
	v_pk_mul_f32 v[66:67], v[148:149], v[60:61] op_sel_hi:[0,1]
	v_pk_mul_f32 v[60:61], v[148:149], v[58:59] op_sel_hi:[0,1]
	v_cvt_pk_bf16_f32 v58, v62, v63
	v_cvt_pk_bf16_f32 v59, v64, v65
	v_cvt_pk_bf16_f32 v60, v60, v61
	v_cvt_pk_bf16_f32 v61, v66, v67
	ds_write_b128 v153, v[58:61]
	v_pk_mul_f32 v[58:59], v[148:149], v[52:53] op_sel_hi:[0,1]
	v_pk_mul_f32 v[52:53], v[148:149], v[50:51] op_sel_hi:[0,1]
	v_pk_mul_f32 v[56:57], v[148:149], v[56:57] op_sel_hi:[0,1]
	v_pk_mul_f32 v[54:55], v[148:149], v[54:55] op_sel_hi:[0,1]
	v_cvt_pk_bf16_f32 v50, v54, v55
	v_cvt_pk_bf16_f32 v51, v56, v57
	v_cvt_pk_bf16_f32 v52, v52, v53
	v_cvt_pk_bf16_f32 v53, v58, v59
	ds_write_b128 v153, v[50:53] offset:64
	s_waitcnt lgkmcnt(2)
	global_store_dwordx4 v[90:91], v[168:171], off offset:2048 nt
	global_store_dwordx4 v[90:91], v[172:175], off offset:3072 nt
	ds_read_b128 v[160:163], v154
	ds_read_b128 v[164:167], v154 offset:1152
	v_add_co_u32_e32 v58, vcc, s52, v122
	v_pk_mul_f32 v[48:49], v[148:149], v[48:49] op_sel_hi:[0,1]
	s_nop 0
	v_addc_co_u32_e32 v59, vcc, 0, v123, vcc
	v_add_co_u32_e32 v60, vcc, s59, v122
	v_pk_mul_f32 v[46:47], v[148:149], v[46:47] op_sel_hi:[0,1]
	s_nop 0
	v_addc_co_u32_e32 v61, vcc, 0, v123, vcc
	v_pk_mul_f32 v[40:41], v[148:149], v[40:41] op_sel_hi:[0,1]
	v_pk_mul_f32 v[50:51], v[148:149], v[44:45] op_sel_hi:[0,1]
	v_pk_mul_f32 v[44:45], v[148:149], v[42:43] op_sel_hi:[0,1]
	v_cvt_pk_bf16_f32 v42, v46, v47
	v_cvt_pk_bf16_f32 v43, v48, v49
	v_cvt_pk_bf16_f32 v44, v44, v45
	v_cvt_pk_bf16_f32 v45, v50, v51
	ds_write_b128 v153, v[42:45]
	v_pk_mul_f32 v[42:43], v[148:149], v[32:33] op_sel_hi:[0,1]
	v_pk_mul_f32 v[32:33], v[148:149], v[30:31] op_sel_hi:[0,1]
	v_pk_mul_f32 v[38:39], v[148:149], v[38:39] op_sel_hi:[0,1]
	v_cvt_pk_bf16_f32 v30, v38, v39
	v_cvt_pk_bf16_f32 v31, v40, v41
	v_cvt_pk_bf16_f32 v32, v32, v33
	v_cvt_pk_bf16_f32 v33, v42, v43
	ds_write_b128 v153, v[30:33] offset:64
	s_waitcnt lgkmcnt(2)
	global_store_dwordx4 v[60:61], v[160:163], off offset:-4096 nt
	global_store_dwordx4 v[58:59], v[164:167], off offset:1024 nt
	ds_read_b128 v[168:171], v154
	ds_read_b128 v[172:175], v154 offset:1152
	v_pk_mul_f32 v[30:31], v[148:149], v[36:37] op_sel_hi:[0,1]
	v_pk_mul_f32 v[32:33], v[148:149], v[34:35] op_sel_hi:[0,1]
	v_pk_mul_f32 v[34:35], v[148:149], v[28:29] op_sel_hi:[0,1]
	v_pk_mul_f32 v[28:29], v[148:149], v[26:27] op_sel_hi:[0,1]
	v_cvt_pk_bf16_f32 v26, v32, v33
	v_cvt_pk_bf16_f32 v27, v30, v31
	v_cvt_pk_bf16_f32 v28, v28, v29
	v_cvt_pk_bf16_f32 v29, v34, v35
	ds_write_b128 v153, v[26:29]
	v_pk_mul_f32 v[26:27], v[148:149], v[16:17] op_sel_hi:[0,1]
	v_pk_mul_f32 v[16:17], v[148:149], v[14:15] op_sel_hi:[0,1]
	v_pk_mul_f32 v[24:25], v[148:149], v[24:25] op_sel_hi:[0,1]
	v_pk_mul_f32 v[22:23], v[148:149], v[22:23] op_sel_hi:[0,1]
	v_cvt_pk_bf16_f32 v14, v22, v23
	v_cvt_pk_bf16_f32 v15, v24, v25
	v_cvt_pk_bf16_f32 v16, v16, v17
	v_cvt_pk_bf16_f32 v17, v26, v27
	ds_write_b128 v153, v[14:17] offset:64
	s_waitcnt lgkmcnt(2)
	global_store_dwordx4 v[58:59], v[168:171], off offset:2048 nt
	global_store_dwordx4 v[58:59], v[172:175], off offset:3072 nt
	ds_read_b128 v[160:163], v154
	ds_read_b128 v[164:167], v154 offset:1152
	v_pk_mul_f32 v[14:15], v[148:149], v[20:21] op_sel_hi:[0,1]
	v_pk_mul_f32 v[16:17], v[148:149], v[18:19] op_sel_hi:[0,1]
	v_pk_mul_f32 v[18:19], v[148:149], v[12:13] op_sel_hi:[0,1]
	v_pk_mul_f32 v[12:13], v[148:149], v[10:11] op_sel_hi:[0,1]
	v_cvt_pk_bf16_f32 v10, v16, v17
	v_cvt_pk_bf16_f32 v11, v14, v15
	v_cvt_pk_bf16_f32 v12, v12, v13
	v_cvt_pk_bf16_f32 v13, v18, v19
	ds_write_b128 v153, v[10:13]
	v_pk_mul_f32 v[10:11], v[148:149], v[4:5] op_sel_hi:[0,1]
	v_pk_mul_f32 v[4:5], v[148:149], v[2:3] op_sel_hi:[0,1]
	v_pk_mul_f32 v[8:9], v[148:149], v[8:9] op_sel_hi:[0,1]
	v_pk_mul_f32 v[6:7], v[148:149], v[6:7] op_sel_hi:[0,1]
	v_cvt_pk_bf16_f32 v2, v6, v7
	v_cvt_pk_bf16_f32 v3, v8, v9
	v_cvt_pk_bf16_f32 v4, v4, v5
	v_cvt_pk_bf16_f32 v5, v10, v11
	ds_write_b128 v153, v[2:5] offset:64
	s_waitcnt lgkmcnt(2)
	global_store_dwordx4 v[60:61], v[160:163], off nt
	global_store_dwordx4 v[60:61], v[164:167], off offset:1024 nt
	ds_read_b128 v[168:171], v154
	ds_read_b128 v[172:175], v154 offset:1152
	s_andn2_b64 vcc, exec, s[4:5]
	s_mov_b64 s[4:5], -1
	s_waitcnt lgkmcnt(0)
	global_store_dwordx4 v[60:61], v[168:171], off offset:2048 nt
	global_store_dwordx4 v[60:61], v[172:175], off offset:3072 nt

; __device__ __forceinline__ size_t tm_block(int pm, int ct, int nct) { return ((size_t)pm * nct + ct) * 32768; }
; __device__ __forceinline__ u32x4 pack8(const f32x4& v0, const f32x4& v1) { u32x4 w; w.x = cvt_pk_bf16(v0[0], v0[1]); w.y = cvt_pk_bf16(v0[2], v0[3]); w.z = cvt_pk_bf16(v1[0], v1[1]); w.w = cvt_pk_bf16(v1[2], v1[3]); return w; }
;     __device__ __forceinline__ void operator()(const f32x4 (&acc)[2][2][4][2], const Unit& u, int wr, int wc, int fr, int fq) const {
;         const PieceOut po(scr, O, tm_block(u.pm, u.pn * 4 + wc, nct), wr, wc, fr, fq);
;         const float qs = (u.pn < 2 || u.pn == 3 || u.pn == 4) ? 0.125f * 1.4426950408889634f : 1.0f;
; #pragma unroll
;         for (int ai = 0; ai < 2; ++ai)
; #pragma unroll
;             for (int m = 0; m < 4; ++m) { po.put(0, pack8(acc[ai][0][m][0] * qs, acc[ai][0][m][1] * qs)); po.put(1, pack8(acc[ai][1][m][0] * qs, acc[ai][1][m][1] * qs)); po.flush<true>(ai, m); }
;     }
.Lp1_epi_plain:
	v_cvt_pk_bf16_f32 v125, v124, v125
	v_cvt_pk_bf16_f32 v124, v122, v123
	v_cvt_pk_bf16_f32 v122, v126, v127
	v_cvt_pk_bf16_f32 v123, v128, v129
	ds_write_b128 v153, v[122:125]
	v_cvt_pk_bf16_f32 v113, v112, v113
	v_cvt_pk_bf16_f32 v112, v110, v111
	v_cvt_pk_bf16_f32 v110, v118, v119
	v_cvt_pk_bf16_f32 v111, v120, v121
	ds_write_b128 v153, v[110:113] offset:64
	ds_read_b128 v[160:163], v154
	ds_read_b128 v[164:167], v154 offset:1152
	v_lshl_add_u64 v[122:123], v[138:139], 0, s[24:25]
	v_cvt_pk_bf16_f32 v109, v108, v109
	v_cvt_pk_bf16_f32 v108, v106, v107
	v_cvt_pk_bf16_f32 v106, v114, v115
	v_cvt_pk_bf16_f32 v107, v116, v117
	ds_write_b128 v153, v[106:109]
	v_cvt_pk_bf16_f32 v97, v96, v97
	v_cvt_pk_bf16_f32 v96, v94, v95
	v_cvt_pk_bf16_f32 v94, v102, v103
	v_cvt_pk_bf16_f32 v95, v104, v105
	ds_write_b128 v153, v[94:97] offset:64
	s_waitcnt lgkmcnt(2)
	global_store_dwordx4 v[122:123], v[160:163], off nt
	global_store_dwordx4 v[122:123], v[164:167], off offset:1024 nt
	ds_read_b128 v[168:171], v154
	ds_read_b128 v[172:175], v154 offset:1152
	v_cvt_pk_bf16_f32 v93, v92, v93
	v_cvt_pk_bf16_f32 v92, v90, v91
	v_cvt_pk_bf16_f32 v90, v98, v99
	v_cvt_pk_bf16_f32 v91, v100, v101
	ds_write_b128 v153, v[90:93]
	v_cvt_pk_bf16_f32 v85, v84, v85
	v_cvt_pk_bf16_f32 v84, v82, v83
	v_cvt_pk_bf16_f32 v82, v86, v87
	v_cvt_pk_bf16_f32 v83, v88, v89
	ds_write_b128 v153, v[82:85] offset:64
	s_waitcnt lgkmcnt(2)
	global_store_dwordx4 v[122:123], v[168:171], off offset:2048 nt
	global_store_dwordx4 v[122:123], v[172:175], off offset:3072 nt
	ds_read_b128 v[160:163], v154
	ds_read_b128 v[164:167], v154 offset:1152
	v_add_co_u32_e32 v90, vcc, s58, v122
	s_nop 0
	s_nop 0
	v_addc_co_u32_e32 v91, vcc, 0, v123, vcc
	v_cvt_pk_bf16_f32 v77, v76, v77
	v_cvt_pk_bf16_f32 v76, v74, v75
	v_cvt_pk_bf16_f32 v74, v78, v79
	v_cvt_pk_bf16_f32 v75, v80, v81
	ds_write_b128 v153, v[74:77]
	v_cvt_pk_bf16_f32 v69, v68, v69
	v_cvt_pk_bf16_f32 v68, v66, v67
	v_cvt_pk_bf16_f32 v66, v70, v71
	v_cvt_pk_bf16_f32 v67, v72, v73
	ds_write_b128 v153, v[66:69] offset:64
	s_waitcnt lgkmcnt(2)
	global_store_dwordx4 v[90:91], v[160:163], off nt
	global_store_dwordx4 v[90:91], v[164:167], off offset:1024 nt
	ds_read_b128 v[168:171], v154
	ds_read_b128 v[172:175], v154 offset:1152
	v_cvt_pk_bf16_f32 v61, v60, v61
	v_cvt_pk_bf16_f32 v60, v58, v59
	v_cvt_pk_bf16_f32 v58, v62, v63
	v_cvt_pk_bf16_f32 v59, v64, v65
	ds_write_b128 v153, v[58:61]
	v_cvt_pk_bf16_f32 v53, v52, v53
	v_cvt_pk_bf16_f32 v52, v50, v51
	v_cvt_pk_bf16_f32 v50, v54, v55
	v_cvt_pk_bf16_f32 v51, v56, v57
	ds_write_b128 v153, v[50:53] offset:64
	s_waitcnt lgkmcnt(2)
	global_store_dwordx4 v[90:91], v[168:171], off offset:2048 nt
	global_store_dwordx4 v[90:91], v[172:175], off offset:3072 nt
	ds_read_b128 v[160:163], v154
	ds_read_b128 v[164:167], v154 offset:1152
	v_add_co_u32_e32 v58, vcc, s52, v122
	s_nop 0
	s_nop 0
	v_addc_co_u32_e32 v59, vcc, 0, v123, vcc
	v_add_co_u32_e32 v60, vcc, s59, v122
	s_nop 0
	s_nop 0
	v_addc_co_u32_e32 v61, vcc, 0, v123, vcc
	v_cvt_pk_bf16_f32 v45, v44, v45
	v_cvt_pk_bf16_f32 v44, v42, v43
	v_cvt_pk_bf16_f32 v42, v46, v47
	v_cvt_pk_bf16_f32 v43, v48, v49
	ds_write_b128 v153, v[42:45]
	v_cvt_pk_bf16_f32 v33, v32, v33
	v_cvt_pk_bf16_f32 v32, v30, v31
	v_cvt_pk_bf16_f32 v30, v38, v39
	v_cvt_pk_bf16_f32 v31, v40, v41
	ds_write_b128 v153, v[30:33] offset:64
	s_waitcnt lgkmcnt(2)
	global_store_dwordx4 v[60:61], v[160:163], off offset:-4096 nt
	global_store_dwordx4 v[58:59], v[164:167], off offset:1024 nt
	ds_read_b128 v[168:171], v154
	ds_read_b128 v[172:175], v154 offset:1152
	v_cvt_pk_bf16_f32 v29, v28, v29
	v_cvt_pk_bf16_f32 v28, v26, v27
	v_cvt_pk_bf16_f32 v26, v34, v35
	v_cvt_pk_bf16_f32 v27, v36, v37
	ds_write_b128 v153, v[26:29]
	v_cvt_pk_bf16_f32 v17, v16, v17
	v_cvt_pk_bf16_f32 v16, v14, v15
	v_cvt_pk_bf16_f32 v14, v22, v23
	v_cvt_pk_bf16_f32 v15, v24, v25
	ds_write_b128 v153, v[14:17] offset:64
	s_waitcnt lgkmcnt(2)
	global_store_dwordx4 v[58:59], v[168:171], off offset:2048 nt
	global_store_dwordx4 v[58:59], v[172:175], off offset:3072 nt
	ds_read_b128 v[160:163], v154
	ds_read_b128 v[164:167], v154 offset:1152
	v_cvt_pk_bf16_f32 v13, v12, v13
	v_cvt_pk_bf16_f32 v12, v10, v11
	v_cvt_pk_bf16_f32 v10, v18, v19
	v_cvt_pk_bf16_f32 v11, v20, v21
	ds_write_b128 v153, v[10:13]
	v_cvt_pk_bf16_f32 v5, v4, v5
	v_cvt_pk_bf16_f32 v4, v2, v3
	v_cvt_pk_bf16_f32 v2, v6, v7
	v_cvt_pk_bf16_f32 v3, v8, v9
	ds_write_b128 v153, v[2:5] offset:64
	s_waitcnt lgkmcnt(2)
	global_store_dwordx4 v[60:61], v[160:163], off nt
	global_store_dwordx4 v[60:61], v[164:167], off offset:1024 nt
	ds_read_b128 v[168:171], v154
	ds_read_b128 v[172:175], v154 offset:1152
	s_andn2_b64 vcc, exec, s[4:5]
	s_mov_b64 s[4:5], -1
	s_waitcnt lgkmcnt(0)
	global_store_dwordx4 v[60:61], v[168:171], off offset:2048 nt
	global_store_dwordx4 v[60:61], v[172:175], off offset:3072 nt
	s_branch .Lp1_epi_join
